# in-proj K-loop: LDS fragment reads use immediate offsets (8 fewer address adds per step)
# baseline (speedup 1.0000x reference)
; #define MFMA(a, b, c) __builtin_amdgcn_mfma_f32_32x32x16_bf16((a), (b), (c), 0, 0, 0)
; DI void gemm_big(const bfr* __restrict__ A, size_t sa, const bfr* __restrict__ Bt, size_t sb, int K, f32x16 (&acc)[2][4], unsigned char* base) {
;     ...
;   for (int kt = 0; kt < nk; ++kt) {
;     if (kt + 1 < nk) asm volatile("s_waitcnt vmcnt(6)" ::: "memory");
;     else asm volatile("s_waitcnt vmcnt(0)" ::: "memory");
;     __builtin_amdgcn_s_barrier();
;     const unsigned cur = lbase + bc * BUFSZ;
;     bf16x8 af[2][2], bq[2][4];
; #pragma unroll
;     for (int ks = 0; ks < 2; ++ks) {
;       const unsigned so = cur + lane_off + ((((ks * 2) | h) ^ x) << 4);
; #pragma unroll
;       for (int i = 0; i < 2; ++i) af[ks][i] = lds_read16_asm(so + (wm * 16 + i * 8) * 256);
; #pragma unroll
;       for (int i = 0; i < 4; ++i) bq[ks][i] = lds_read16_asm(so + 8192 + (wn * 32 + i * 8) * 256);
;     }
;     if (kt + 2 < nk) {
;       const int bn = bc >= 1 ? bc - 1 : 2;
;       unsigned char* nxt = base + bn * BUFSZ;
;       stage_tile32<128>(A + (size_t)(kt + 2) * sa, nxt, tid);
;       stage_tile32<256>(Bt + (size_t)(kt + 2) * sb, nxt + 8192, tid);
;     }
;     asm volatile("s_waitcnt lgkmcnt(0)"
;                  : "+v"(af[0][0]), "+v"(af[0][1]), "+v"(af[1][0]), "+v"(af[1][1]), "+v"(bq[0][0]), "+v"(bq[0][1]), "+v"(bq[0][2]), "+v"(bq[0][3]),
;                    "+v"(bq[1][0]), "+v"(bq[1][1]), "+v"(bq[1][2]), "+v"(bq[1][3])
;                  :: "memory");
; #pragma unroll
;     for (int ks = 0; ks < 2; ++ks)
; #pragma unroll
;       for (int mi = 0; mi < 2; ++mi)
; #pragma unroll
;         for (int ni = 0; ni < 4; ++ni) acc[mi][ni] = MFMA(af[ks][mi], bq[ks][ni], acc[mi][ni]);
;     bc = bc == 2 ? 0 : bc + 1;
;   }
.LBB0_162:
	s_mul_i32 s6, s5, 0x6000
	v_or_b32_e32 v128, s6, v239
	v_add_u32_e32 v129, v128, v233
	s_addk_i32 s6, 0xa000
	v_add_u32_e32 v130, v129, v241
	s_cmp_gt_i32 s5, 0
	s_waitcnt vmcnt(6)
	s_barrier
	ds_read_b128 v[152:155], v130
	ds_read_b128 v[132:135], v130 offset:2048
	v_add_u32_e32 v129, v129, v240
	v_add_u32_e32 v140, v128, v242
	s_cselect_b32 s6, s6, 0xc000
	ds_read_b128 v[160:163], v129
	ds_read_b128 v[164:167], v129 offset:2048
	ds_read_b128 v[168:171], v129 offset:4096
	ds_read_b128 v[172:175], v129 offset:6144
	v_add_u32_e32 v128, v140, v241
	v_add_u32_e32 v156, v140, v240
	ds_read_b128 v[136:139], v128
	ds_read_b128 v[128:131], v128 offset:2048
	ds_read_b128 v[140:143], v156
	ds_read_b128 v[144:147], v156 offset:2048
	ds_read_b128 v[148:151], v156 offset:4096
	ds_read_b128 v[156:159], v156 offset:6144
	v_add_u32_e32 v208, s6, v237
	v_add_u32_e32 v221, s6, v238
	v_lshl_add_u64 v[250:251], s[14:15], 0, v[198:199]
	v_readfirstlane_b32 s7, v208
	s_waitcnt lgkmcnt(6)
	v_mfma_f32_32x32x16_bf16 v[112:127], v[152:155], v[160:163], v[112:127]
	s_mov_b32 m0, s7
	v_readfirstlane_b32 s7, v221
	v_add_u32_e32 v208, 0x2000, v208
	global_load_lds_dwordx4 v[250:251], off
	v_mfma_f32_32x32x16_bf16 v[96:111], v[152:155], v[164:167], v[96:111]
	v_lshl_add_u64 v[250:251], s[14:15], 0, v[196:197]
	s_mov_b32 m0, s7
	v_readfirstlane_b32 s7, v208
	v_add_u32_e32 v208, 0x2000, v221
	global_load_lds_dwordx4 v[250:251], off
	v_mfma_f32_32x32x16_bf16 v[80:95], v[152:155], v[168:171], v[80:95]
	v_mfma_f32_32x32x16_bf16 v[64:79], v[152:155], v[172:175], v[64:79]
	s_mov_b32 m0, s7
	v_readfirstlane_b32 s7, v208
	v_add_u32_e32 v208, s6, v232
	v_lshl_add_u64 v[250:251], s[14:15], 0, v[194:195]
	v_add_u32_e32 v208, 0x2000, v208
	global_load_lds_dwordx4 v[250:251], off
	v_mfma_f32_32x32x16_bf16 v[48:63], v[132:135], v[160:163], v[48:63]
	v_mfma_f32_32x32x16_bf16 v[32:47], v[132:135], v[164:167], v[32:47]
	s_mov_b32 m0, s7
	v_readfirstlane_b32 s7, v208
	v_add_u32_e32 v208, s6, v219
	v_lshl_add_u64 v[250:251], s[14:15], 0, v[192:193]
	v_add_u32_e32 v208, 0x2000, v208
	global_load_lds_dwordx4 v[250:251], off
	v_mfma_f32_32x32x16_bf16 v[16:31], v[132:135], v[168:171], v[16:31]
	v_mfma_f32_32x32x16_bf16 v[0:15], v[132:135], v[172:175], v[0:15]
	v_lshl_add_u64 v[250:251], s[14:15], 0, v[190:191]
	s_mov_b32 m0, s7
	v_readfirstlane_b32 s6, v208
	global_load_lds_dwordx4 v[250:251], off
	s_waitcnt lgkmcnt(0)
	v_mfma_f32_32x32x16_bf16 v[112:127], v[136:139], v[140:143], v[112:127]
	v_lshl_add_u64 v[250:251], s[14:15], 0, v[188:189]
	s_mov_b32 m0, s6
	s_add_i32 s6, s5, 1
	global_load_lds_dwordx4 v[250:251], off
	v_mfma_f32_32x32x16_bf16 v[96:111], v[136:139], v[144:147], v[96:111]
	s_cmp_lg_u32 s5, 2
	s_cselect_b32 s5, s6, 0
	s_add_i32 s4, s4, -1
	v_lshl_add_u64 v[188:189], v[188:189], 0, s[96:97]
	v_lshl_add_u64 v[190:191], v[190:191], 0, s[96:97]
	v_mfma_f32_32x32x16_bf16 v[80:95], v[136:139], v[148:151], v[80:95]
	v_lshl_add_u64 v[192:193], v[192:193], 0, s[96:97]
	v_lshl_add_u64 v[194:195], v[194:195], 0, s[96:97]
	v_mfma_f32_32x32x16_bf16 v[64:79], v[136:139], v[156:159], v[64:79]
	v_lshl_add_u64 v[196:197], v[196:197], 0, s[0:1]
	v_lshl_add_u64 v[198:199], v[198:199], 0, s[0:1]
	s_cmp_lg_u32 s4, 0
	v_mfma_f32_32x32x16_bf16 v[48:63], v[128:131], v[140:143], v[48:63]
	v_mfma_f32_32x32x16_bf16 v[32:47], v[128:131], v[144:147], v[32:47]
	v_mfma_f32_32x32x16_bf16 v[16:31], v[128:131], v[148:151], v[16:31]
	v_mfma_f32_32x32x16_bf16 v[0:15], v[128:131], v[156:159], v[0:15]
	s_cbranch_scc1 .LBB0_162
	v_or_b32_e32 v152, 0xc000, v239
	v_add_u32_e32 v136, v152, v233
	v_add_u32_e32 v132, v136, v241
	s_waitcnt vmcnt(6)
	s_barrier
	ds_read_b128 v[128:131], v132
	v_add_u32_e32 v132, 0x800, v132
	v_add_u32_e32 v148, v136, v240
	v_add_u32_e32 v160, v152, v242
	ds_read_b128 v[132:135], v132
	ds_read_b128 v[136:139], v148
	v_add_u32_e32 v140, 0x800, v148
	v_add_u32_e32 v144, 0x1000, v148
	v_add_u32_e32 v148, 0x1800, v148
	v_add_u32_e32 v156, v160, v241
	ds_read_b128 v[140:143], v140
	ds_read_b128 v[144:147], v144
	ds_read_b128 v[148:151], v148
	ds_read_b128 v[152:155], v156
	v_add_u32_e32 v156, 0x800, v156
	v_add_u32_e32 v172, v160, v240
	ds_read_b128 v[156:159], v156
	ds_read_b128 v[160:163], v172
	v_add_u32_e32 v164, 0x800, v172
	v_add_u32_e32 v168, 0x1000, v172
	v_add_u32_e32 v172, 0x1800, v172
	ds_read_b128 v[164:167], v164
	ds_read_b128 v[168:171], v168
	ds_read_b128 v[172:175], v172
	s_mul_i32 s4, s20, 0xf1
	s_waitcnt lgkmcnt(0)
	s_waitcnt vmcnt(0)
	s_barrier
; #define MFMA(a, b, c) __builtin_amdgcn_mfma_f32_32x32x16_bf16((a), (b), (c), 0, 0, 0)
; DI unsigned pk2(float a, float b) { f2_t v = {a, b}; bf2_t r = __builtin_convertvector(v, bf2_t); return __builtin_bit_cast(unsigned, r); }
; DI void gemm_big(const bfr* __restrict__ A, size_t sa, const bfr* __restrict__ Bt, size_t sb, int K, f32x16 (&acc)[2][4], unsigned char* base) {
;     ...
; #pragma unroll
;     for (int ks = 0; ks < 2; ++ks)
; #pragma unroll
;       for (int mi = 0; mi < 2; ++mi)
; #pragma unroll
;         for (int ni = 0; ni < 4; ++ni) acc[mi][ni] = MFMA(af[ks][mi], bq[ks][ni], acc[mi][ni]);
; DI void phase_inproj(const Params& p, int l, unsigned char* smem) {
;     ...
;     gemm_big(H + (size_t)m0 * 32, (size_t)NTOK * 32, W + (size_t)n0 * 32, (size_t)NWIN * 32, DM, acc, smem);
;     const int b = m0 / SP, s0 = m0 - b * SP;
;     const bool isctx = s0 < CTX;
; #pragma unroll
;     for (int mi = 0; mi < 2; ++mi)
; #pragma unroll
;       for (int ni = 0; ni < 4; ++ni) {
;         const int cb = n0 + wn * 128 + ni * 32, col = cb + l31, rb = wm * 64 + mi * 32;
;         const f32x16& a = acc[mi][ni];
;         if (n0 < 1024) {
;           const int part = n0 >> 9, ch = col & 511;
; #pragma unroll
;           for (int g = 0; g < 4; ++g) {
;             const int rr = rb + 8 * g + 4 * h;
;             u32x2 w; w[0] = pk2(a[4 * g], a[4 * g + 1]); w[1] = pk2(a[4 * g + 2], a[4 * g + 3]);
;             if (isctx) *(u32x2*)(FTC + ((size_t)(b * 512 + ch)) * 512 + part * 256 + s0 + rr) = w;
;             else *(u32x2*)(FTL + ((size_t)(b * 512 + ch)) * 8192 + part * 4096 + (s0 - CTX) + rr) = w;
;           }
;         } else if (n0 >= C_DAV && n0 < C_DAZ) {
	v_mfma_f32_32x32x16_bf16 v[112:127], v[128:131], v[136:139], v[112:127]
	s_bfe_u32 s11, s4, 0x3000d
	s_mul_i32 s4, s11, 0xffffef00
	s_add_i32 s10, s4, s44
	s_cmpk_lt_i32 s10, 0x100
	s_cselect_b64 s[4:5], -1, 0
	s_cmpk_gt_i32 s10, 0xff
	s_cselect_b64 s[6:7], -1, 0
	v_mfma_f32_32x32x16_bf16 v[96:111], v[128:131], v[140:143], v[96:111]
	s_cmp_gt_i32 s46, 3
	v_mfma_f32_32x32x16_bf16 v[80:95], v[128:131], v[144:147], v[80:95]
	v_mfma_f32_32x32x16_bf16 v[64:79], v[128:131], v[148:151], v[64:79]
	v_mfma_f32_32x32x16_bf16 v[48:63], v[132:135], v[136:139], v[48:63]
	v_add_u32_e32 v136, v239, v233
	v_mfma_f32_32x32x16_bf16 v[32:47], v[132:135], v[140:143], v[32:47]
	v_mfma_f32_32x32x16_bf16 v[16:31], v[132:135], v[144:147], v[16:31]
	v_mfma_f32_32x32x16_bf16 v[0:15], v[132:135], v[148:151], v[0:15]
	v_add_u32_e32 v132, v136, v241
	ds_read_b128 v[128:131], v132
	v_add_u32_e32 v132, 0x800, v132
	v_add_u32_e32 v148, v136, v240
	ds_read_b128 v[132:135], v132
	ds_read_b128 v[136:139], v148
	v_add_u32_e32 v140, 0x800, v148
	v_mfma_f32_32x32x16_bf16 v[112:127], v[152:155], v[160:163], v[112:127]
	v_add_u32_e32 v144, 0x1000, v148
	v_add_u32_e32 v148, 0x1800, v148
	ds_read_b128 v[140:143], v140
	ds_read_b128 v[144:147], v144
	ds_read_b128 v[148:151], v148
	v_mfma_f32_32x32x16_bf16 v[96:111], v[152:155], v[164:167], v[96:111]
	v_mfma_f32_32x32x16_bf16 v[80:95], v[152:155], v[168:171], v[80:95]
	v_mfma_f32_32x32x16_bf16 v[64:79], v[152:155], v[172:175], v[64:79]
	v_mfma_f32_32x32x16_bf16 v[48:63], v[156:159], v[160:163], v[48:63]
	v_add_u32_e32 v160, v242, v239
	v_mfma_f32_32x32x16_bf16 v[32:47], v[156:159], v[164:167], v[32:47]
	v_mfma_f32_32x32x16_bf16 v[16:31], v[156:159], v[168:171], v[16:31]
	v_mfma_f32_32x32x16_bf16 v[0:15], v[156:159], v[172:175], v[0:15]
	v_add_u32_e32 v156, v160, v241
	ds_read_b128 v[152:155], v156
	v_add_u32_e32 v156, 0x800, v156
	v_add_u32_e32 v172, v160, v240
	ds_read_b128 v[156:159], v156
	ds_read_b128 v[160:163], v172
	v_add_u32_e32 v164, 0x800, v172
	v_add_u32_e32 v168, 0x1000, v172
	v_add_u32_e32 v172, 0x1800, v172
	ds_read_b128 v[164:167], v164
	ds_read_b128 v[168:171], v168
	ds_read_b128 v[172:175], v172
	s_nop 0
	s_waitcnt lgkmcnt(0)
	s_nop 0
	v_mfma_f32_32x32x16_bf16 v[112:127], v[128:131], v[136:139], v[112:127]
	v_mfma_f32_32x32x16_bf16 v[96:111], v[128:131], v[140:143], v[96:111]
	v_mfma_f32_32x32x16_bf16 v[80:95], v[128:131], v[144:147], v[80:95]
	v_mfma_f32_32x32x16_bf16 v[64:79], v[128:131], v[148:151], v[64:79]
	v_or_b32_e32 v128, s8, v200
	s_cselect_b64 s[8:9], -1, 0
	s_and_b32 s18, s46, 0x7ffffffe
	s_cmp_lg_u32 s18, 28
	s_cselect_b64 s[26:27], -1, 0
	s_and_b32 s18, s46, 0x7ffffffc
	s_cmp_eq_u32 s18, 24
	s_cselect_b64 s[18:19], -1, 0
	s_lshl_b32 s51, s11, 9
	s_ashr_i32 s11, s10, 31
	v_mfma_f32_32x32x16_bf16 v[48:63], v[132:135], v[136:139], v[48:63]
	s_and_b64 s[24:25], s[18:19], s[6:7]
	s_add_i32 s50, s10, 0xffffff00
	s_add_i32 s47, s51, 0xffffe400
	s_lshl_b64 s[20:21], s[10:11], 1
	s_add_u32 s22, s38, s20
	s_addc_u32 s23, s39, s21
	s_ashr_i32 s28, s46, 1
	v_mfma_f32_32x32x16_bf16 v[32:47], v[132:135], v[140:143], v[32:47]
	s_lshl_b32 s18, s28, 12
	s_ashr_i32 s19, s18, 31
	s_lshl_b64 s[18:19], s[18:19], 1
	s_add_u32 s18, s14, s18
	s_mov_b32 s11, s45
	s_addc_u32 s19, s15, s19
	s_lshl_b64 s[10:11], s[10:11], 1
	v_mfma_f32_32x32x16_bf16 v[16:31], v[132:135], v[144:147], v[16:31]
	s_add_u32 s18, s18, s10
	s_addc_u32 s19, s19, s11
	s_lshl_b32 s10, s28, 8
	s_ashr_i32 s11, s10, 31
	s_lshl_b64 s[10:11], s[10:11], 1
	s_add_u32 s10, s36, s10
	s_addc_u32 s11, s37, s11
	v_mfma_f32_32x32x16_bf16 v[0:15], v[132:135], v[148:151], v[0:15]
	v_or_b32_e32 v136, s44, v202
	s_add_u32 s20, s10, s20
	s_addc_u32 s21, s11, s21
	v_add_u32_e32 v130, v136, v201
	s_mov_b64 s[10:11], -1
	s_and_b64 vcc, exec, s[8:9]
	v_mfma_f32_32x32x16_bf16 v[112:127], v[152:155], v[160:163], v[112:127]
	v_mfma_f32_32x32x16_bf16 v[96:111], v[152:155], v[164:167], v[96:111]
	v_mfma_f32_32x32x16_bf16 v[80:95], v[152:155], v[168:171], v[80:95]
	v_mfma_f32_32x32x16_bf16 v[64:79], v[152:155], v[172:175], v[64:79]
	v_mfma_f32_32x32x16_bf16 v[48:63], v[156:159], v[160:163], v[48:63]
	v_mfma_f32_32x32x16_bf16 v[32:47], v[156:159], v[164:167], v[32:47]
	v_mfma_f32_32x32x16_bf16 v[16:31], v[156:159], v[168:171], v[16:31]
	v_mfma_f32_32x32x16_bf16 v[0:15], v[156:159], v[172:175], v[0:15]
	s_cbranch_vccz .LBB0_173
	s_and_b64 vcc, exec, s[26:27]
	s_cbranch_vccz .LBB0_170
	s_and_b64 vcc, exec, s[24:25]
	s_cbranch_vccz .LBB0_167
; DI bfr f2bf(float a) { return (bfr)(pk2(a, 0.f) & 0xffffu); }
; DI int crow(int r, int h) { return (r & 3) + 8 * (r >> 2) + 4 * h; }
; DI void phase_inproj(const Params& p, int l, unsigned char* smem) {
;     ...
;         } else if (n0 >= C_DAQ && n0 < C_DAV && !isctx) {
;           const int aidx = ((cb >> 5) & 1) * 16 + (l31 & 15);
;           const bool lo = (l31 & 16) == 0;
; #pragma unroll
;           for (int r = 0; r < 16; ++r) {
;             const int rr = rb + crow(r, h), pos = s0 - CTX + rr;
;             const float v = a[r], o = __shfl_xor(v, 16);
;             const float cs = ROPE[((size_t)pos * 32 + aidx) * 2], sn = ROPE[((size_t)pos * 32 + aidx) * 2 + 1];
;             const float res = lo ? v * cs - o * sn : v * cs + o * sn;
;             P[(size_t)(m0 + rr) * PLD + col] = f2bf(res);
;           }
	s_mov_b64 s[10:11], 0
	v_mbcnt_lo_u32_b32 v250, -1, 0
	v_mbcnt_hi_u32_b32 v250, -1, v250
	v_and_b32_e32 v251, 15, v216
	v_xor_b32_e32 v250, 16, v250
	v_lshlrev_b32_e32 v251, 3, v251
	v_lshlrev_b32_e32 v250, 2, v250
	v_add_u32_e32 v251, 0x53b50000, v251
	v_lshlrev_b32_e32 v208, 1, v128
	v_add_u32_e32 v208, 0xcc00000, v208
	v_add_u32_e32 v130, s50, v176
	v_lshl_add_u32 v130, v130, 8, v251
	global_load_dwordx2 v[130:131], v130, s[84:85]
	v_add_u32_e32 v132, s50, v203
	v_lshl_add_u32 v132, v132, 8, v251
	global_load_dwordx2 v[132:133], v132, s[84:85]
	v_add_u32_e32 v134, s50, v204
	v_lshl_add_u32 v134, v134, 8, v251
	global_load_dwordx2 v[134:135], v134, s[84:85]
	v_add_u32_e32 v136, s50, v205
	v_lshl_add_u32 v136, v136, 8, v251
	global_load_dwordx2 v[136:137], v136, s[84:85]
	v_add_u32_e32 v138, s50, v206
	v_lshl_add_u32 v138, v138, 8, v251
	global_load_dwordx2 v[138:139], v138, s[84:85]
	v_add_u32_e32 v140, s50, v207
	v_lshl_add_u32 v140, v140, 8, v251
	global_load_dwordx2 v[140:141], v140, s[84:85]
	v_add_u32_e32 v142, s50, v211
	v_lshl_add_u32 v142, v142, 8, v251
	global_load_dwordx2 v[142:143], v142, s[84:85]
	v_add_u32_e32 v144, s50, v212
	v_lshl_add_u32 v144, v144, 8, v251
	global_load_dwordx2 v[144:145], v144, s[84:85]
	v_add_u32_e32 v146, s50, v213
	v_lshl_add_u32 v146, v146, 8, v251
	global_load_dwordx2 v[146:147], v146, s[84:85]
	v_add_u32_e32 v148, s50, v214
	v_lshl_add_u32 v148, v148, 8, v251
	global_load_dwordx2 v[148:149], v148, s[84:85]
	v_add_u32_e32 v150, s50, v215
	v_lshl_add_u32 v150, v150, 8, v251
	global_load_dwordx2 v[150:151], v150, s[84:85]
	v_add_u32_e32 v152, s50, v244
	v_lshl_add_u32 v152, v152, 8, v251
	global_load_dwordx2 v[152:153], v152, s[84:85]
	v_add_u32_e32 v154, s50, v180
	v_lshl_add_u32 v154, v154, 8, v251
	global_load_dwordx2 v[154:155], v154, s[84:85]
	v_add_u32_e32 v156, s50, v245
	v_lshl_add_u32 v156, v156, 8, v251
	global_load_dwordx2 v[156:157], v156, s[84:85]
	v_add_u32_e32 v158, s50, v246
	v_lshl_add_u32 v158, v158, 8, v251
	global_load_dwordx2 v[158:159], v158, s[84:85]
	v_add_u32_e32 v160, s50, v247
	v_lshl_add_u32 v160, v160, 8, v251
	global_load_dwordx2 v[160:161], v160, s[84:85]
	ds_bpermute_b32 v162, v250, v112
	ds_bpermute_b32 v163, v250, v113
	ds_bpermute_b32 v164, v250, v114
	ds_bpermute_b32 v165, v250, v115
	ds_bpermute_b32 v166, v250, v116
	ds_bpermute_b32 v167, v250, v117
	ds_bpermute_b32 v168, v250, v118
	ds_bpermute_b32 v169, v250, v119
	ds_bpermute_b32 v170, v250, v120
	ds_bpermute_b32 v171, v250, v121
	ds_bpermute_b32 v172, v250, v122
	ds_bpermute_b32 v173, v250, v123
	ds_bpermute_b32 v174, v250, v124
	ds_bpermute_b32 v175, v250, v125
	ds_bpermute_b32 v129, v250, v126
	ds_bpermute_b32 v221, v250, v127
	s_waitcnt vmcnt(0) lgkmcnt(0)
	v_mul_f32_e32 v162, v131, v162
	v_cndmask_b32_e64 v162, v162, -v162, s[12:13]
	v_fmac_f32_e32 v162, v112, v130
	v_add_u32_e32 v130, s44, v176
	v_cvt_pk_bf16_f32 v162, v162, v162
	v_lshl_add_u32 v130, v130, 15, v208
	global_store_short v130, v162, s[84:85]
	v_mul_f32_e32 v163, v133, v163
	v_cndmask_b32_e64 v163, v163, -v163, s[12:13]
	v_fmac_f32_e32 v163, v113, v132
	v_add_u32_e32 v132, s44, v203
	v_cvt_pk_bf16_f32 v163, v163, v163
	v_lshl_add_u32 v132, v132, 15, v208
	global_store_short v132, v163, s[84:85]
	v_mul_f32_e32 v164, v135, v164
	v_cndmask_b32_e64 v164, v164, -v164, s[12:13]
	v_fmac_f32_e32 v164, v114, v134
	v_add_u32_e32 v134, s44, v204
	v_cvt_pk_bf16_f32 v164, v164, v164
	v_lshl_add_u32 v134, v134, 15, v208
	global_store_short v134, v164, s[84:85]
	v_mul_f32_e32 v165, v137, v165
	v_cndmask_b32_e64 v165, v165, -v165, s[12:13]
	v_fmac_f32_e32 v165, v115, v136
	v_add_u32_e32 v136, s44, v205
	v_cvt_pk_bf16_f32 v165, v165, v165
	v_lshl_add_u32 v136, v136, 15, v208
	global_store_short v136, v165, s[84:85]
	v_mul_f32_e32 v166, v139, v166
	v_cndmask_b32_e64 v166, v166, -v166, s[12:13]
	v_fmac_f32_e32 v166, v116, v138
	v_add_u32_e32 v138, s44, v206
	v_cvt_pk_bf16_f32 v166, v166, v166
	v_lshl_add_u32 v138, v138, 15, v208
	global_store_short v138, v166, s[84:85]
	v_mul_f32_e32 v167, v141, v167
	v_cndmask_b32_e64 v167, v167, -v167, s[12:13]
	v_fmac_f32_e32 v167, v117, v140
	v_add_u32_e32 v140, s44, v207
	v_cvt_pk_bf16_f32 v167, v167, v167
	v_lshl_add_u32 v140, v140, 15, v208
	global_store_short v140, v167, s[84:85]
	v_mul_f32_e32 v168, v143, v168
	v_cndmask_b32_e64 v168, v168, -v168, s[12:13]
	v_fmac_f32_e32 v168, v118, v142
	v_add_u32_e32 v142, s44, v211
	v_cvt_pk_bf16_f32 v168, v168, v168
	v_lshl_add_u32 v142, v142, 15, v208
	global_store_short v142, v168, s[84:85]
	v_mul_f32_e32 v169, v145, v169
	v_cndmask_b32_e64 v169, v169, -v169, s[12:13]
	v_fmac_f32_e32 v169, v119, v144
	v_add_u32_e32 v144, s44, v212
	v_cvt_pk_bf16_f32 v169, v169, v169
	v_lshl_add_u32 v144, v144, 15, v208
	global_store_short v144, v169, s[84:85]
	v_mul_f32_e32 v170, v147, v170
	v_cndmask_b32_e64 v170, v170, -v170, s[12:13]
	v_fmac_f32_e32 v170, v120, v146
	v_add_u32_e32 v146, s44, v213
	v_cvt_pk_bf16_f32 v170, v170, v170
	v_lshl_add_u32 v146, v146, 15, v208
	global_store_short v146, v170, s[84:85]
	v_mul_f32_e32 v171, v149, v171
	v_cndmask_b32_e64 v171, v171, -v171, s[12:13]
	v_fmac_f32_e32 v171, v121, v148
	v_add_u32_e32 v148, s44, v214
	v_cvt_pk_bf16_f32 v171, v171, v171
	v_lshl_add_u32 v148, v148, 15, v208
	global_store_short v148, v171, s[84:85]
	v_mul_f32_e32 v172, v151, v172
	v_cndmask_b32_e64 v172, v172, -v172, s[12:13]
	v_fmac_f32_e32 v172, v122, v150
	v_add_u32_e32 v150, s44, v215
	v_cvt_pk_bf16_f32 v172, v172, v172
	v_lshl_add_u32 v150, v150, 15, v208
	global_store_short v150, v172, s[84:85]
	v_mul_f32_e32 v173, v153, v173
	v_cndmask_b32_e64 v173, v173, -v173, s[12:13]
	v_fmac_f32_e32 v173, v123, v152
	v_add_u32_e32 v152, s44, v244
	v_cvt_pk_bf16_f32 v173, v173, v173
	v_lshl_add_u32 v152, v152, 15, v208
	global_store_short v152, v173, s[84:85]
	v_mul_f32_e32 v174, v155, v174
	v_cndmask_b32_e64 v174, v174, -v174, s[12:13]
	v_fmac_f32_e32 v174, v124, v154
	v_add_u32_e32 v154, s44, v180
	v_cvt_pk_bf16_f32 v174, v174, v174
	v_lshl_add_u32 v154, v154, 15, v208
	global_store_short v154, v174, s[84:85]
	v_mul_f32_e32 v175, v157, v175
	v_cndmask_b32_e64 v175, v175, -v175, s[12:13]
	v_fmac_f32_e32 v175, v125, v156
	v_add_u32_e32 v156, s44, v245
	v_cvt_pk_bf16_f32 v175, v175, v175
	v_lshl_add_u32 v156, v156, 15, v208
	global_store_short v156, v175, s[84:85]
	v_mul_f32_e32 v129, v159, v129
	v_cndmask_b32_e64 v129, v129, -v129, s[12:13]
	v_fmac_f32_e32 v129, v126, v158
	v_add_u32_e32 v158, s44, v246
	v_cvt_pk_bf16_f32 v129, v129, v129
	v_lshl_add_u32 v158, v158, 15, v208
	global_store_short v158, v129, s[84:85]
	v_mul_f32_e32 v221, v161, v221
	v_cndmask_b32_e64 v221, v221, -v221, s[12:13]
	v_fmac_f32_e32 v221, v127, v160
	v_add_u32_e32 v160, s44, v247
	v_cvt_pk_bf16_f32 v221, v221, v221
	v_lshl_add_u32 v160, v160, 15, v208
	global_store_short v160, v221, s[84:85]
